# Epi3 row-statistics exchange by direct slot polling (NaN-initialised slots): no panel counter, two barriers fewer per exchange
# speedup vs baseline: 1.0261x; 1.0144x over previous
.LBB0_286:
	s_or_b64 exec, exec, s[0:1]
	v_readlane_b32 s0, v251, 13
	s_nop 1
	v_add_u32_e32 v3, s0, v21
	v_mul_u32_u24_e32 v40, 48, v3
	s_add_u32 s8, s82, 0x1f510000
	s_addc_u32 s9, s83, 0
	v_mov_b32_e32 v42, 0x7fc00000
	v_mov_b32_e32 v43, v42
	v_mov_b32_e32 v44, v42
	v_mov_b32_e32 v45, v42
	global_store_dwordx4 v40, v[42:45], s[8:9]
	global_store_dwordx4 v40, v[42:45], s[8:9] offset:16
	global_store_dwordx4 v40, v[42:45], s[8:9] offset:32
	s_mov_b32 s0, 0xc0000
	v_cmp_gt_i32_e32 vcc, s0, v3
	s_and_saveexec_b64 s[0:1], vcc
	s_mov_b32 s8, 0x6dc9c883
	s_mov_b32 s9, 0x3fc45f30
	s_mov_b32 s7, 0xc2fc0000
	s_mov_b32 s10, 0x2aaaaaab
	s_cbranch_execz .LBB0_291
	v_readlane_b32 s2, v251, 13
	v_mov_b32_e32 v13, v3
	s_nop 0
	v_add_u16_e32 v12, s2, v21
	s_mov_b64 s[2:3], 0

.LBB0_651:
	s_or_b64 exec, exec, s[0:1]
	s_lshl_b32 s0, s80, 8
	s_or_b32 s0, s0, s58
	v_lshl_add_u32 v190, v3, 3, s0
	v_ashrrev_i32_e32 v3, 31, v2
	v_ashrrev_i32_e32 v189, 31, v188
	v_lshl_add_u64 v[148:149], v[2:3], 0, v[188:189]
	v_ashrrev_i32_e32 v191, 31, v190
	v_readlane_b32 s0, v253, 37
	v_lshlrev_b64 v[148:149], 10, v[148:149]
	v_lshl_add_u64 v[150:151], v[190:191], 0, s[64:65]
	v_readlane_b32 s1, v253, 38
	v_lshl_add_u64 v[194:195], v[150:151], 0, v[148:149]
	v_lshl_add_u64 v[202:203], v[194:195], 1, s[12:13]
	v_lshl_add_u64 v[136:137], v[190:191], 2, s[0:1]
	s_mov_b32 s0, 0x8000
	v_add_co_u32_e32 v148, vcc, s0, v202
	s_mov_b32 s0, 0x10000
	s_nop 0
	v_addc_co_u32_e32 v149, vcc, 0, v203, vcc
	global_load_dwordx4 v[140:143], v[136:137], off offset:16
	global_load_dwordx4 v[144:147], v[136:137], off
	global_load_dwordx4 v[132:135], v[136:137], off offset:528
	s_nop 0
	global_load_dwordx4 v[136:139], v[136:137], off offset:512
	s_nop 0
	global_load_dwordx4 v[160:163], v[202:203], off
	global_load_dwordx4 v[168:171], v[202:203], off offset:256
	global_load_dwordx4 v[172:175], v[148:149], off
	global_load_dwordx4 v[176:179], v[148:149], off offset:256
	v_add_co_u32_e32 v148, vcc, s0, v202
	s_mov_b32 s0, 0x18000
	s_nop 0
	v_addc_co_u32_e32 v149, vcc, 0, v203, vcc
	global_load_dwordx4 v[180:183], v[148:149], off
	global_load_dwordx4 v[164:167], v[148:149], off offset:256
	v_add_co_u32_e32 v148, vcc, s0, v202
	s_ashr_i32 s83, s82, 31
	s_nop 0
	v_addc_co_u32_e32 v149, vcc, 0, v203, vcc
	global_load_dwordx4 v[152:155], v[148:149], off
	s_nop 0
	global_load_dwordx4 v[148:151], v[148:149], off offset:256
	s_lshl_b64 s[0:1], s[82:83], 2
	s_waitcnt vmcnt(12)
	s_add_u32 s2, s49, s0
	s_addc_u32 s3, s60, s1
	s_waitcnt lgkmcnt(0)
	s_mov_b64 s[0:1], exec
.LBB0_673:
	s_or_b64 exec, exec, s[0:1]
	s_mov_b64 s[0:1], 0x8000
	v_lshl_add_u64 v[200:201], v[202:203], 0, s[0:1]
	s_mov_b64 s[0:1], 0x10000
	v_lshl_add_u64 v[198:199], v[202:203], 0, s[0:1]
	s_mov_b64 s[0:1], 0x18000
	v_add_u32_e32 v192, v2, v0
	v_lshl_add_u64 v[196:197], v[202:203], 0, s[0:1]
	v_ashrrev_i32_e32 v193, 31, v192
	s_and_saveexec_b64 s[6:7], s[4:5]
	s_cbranch_execz .LBB0_675
	v_lshl_add_u64 v[156:157], v[192:193], 4, s[36:37]
	s_movk_i32 s81, 0x1000
	s_mov_b64 s[10:11], exec
.Lx1_spin:
	global_load_dword v158, v[156:157], off sc1
	global_load_dword v204, v[156:157], off offset:4 sc1
	global_load_dword v159, v[156:157], off offset:8 sc1
	global_load_dword v205, v[156:157], off offset:12 sc1
	s_waitcnt vmcnt(0)
	v_cmp_u_f32_e32 vcc, v158, v204
	v_cmp_u_f32_e64 s[38:39], v159, v205
	s_or_b64 vcc, vcc, s[38:39]
	s_add_i32 s81, s81, -1
	s_cmp_eq_u32 s81, 0
	s_cbranch_scc1 .Lx1_done
	s_and_b64 exec, exec, vcc
	s_cbranch_execz .Lx1_done
	s_sleep 1
	s_branch .Lx1_spin
.Lx1_done:
	s_mov_b64 exec, s[10:11]
	s_mov_b32 s0, 0xf800000
	s_waitcnt lgkmcnt(0)
	v_pk_add_f32 v[156:157], v[158:159], v[204:205]
	s_nop 0
	v_add_f32_e32 v3, v156, v157
	v_fmamk_f32 v3, v3, 0x3a800000, v217
	v_cmp_gt_f32_e32 vcc, s0, v3
	v_mul_f32_e32 v156, 0x4f800000, v3
	s_nop 0
	v_cndmask_b32_e32 v3, v3, v156, vcc
	v_sqrt_f32_e32 v156, v3
	s_nop 0
	v_add_u32_e32 v157, -1, v156
	v_fma_f32 v158, -v157, v156, v3
	v_cmp_ge_f32_e64 s[0:1], 0, v158
	v_add_u32_e32 v158, 1, v156
	s_nop 0
	v_cndmask_b32_e64 v157, v156, v157, s[0:1]
	v_fma_f32 v156, -v158, v156, v3
	v_cmp_lt_f32_e64 s[0:1], 0, v156
	s_nop 1
	v_cndmask_b32_e64 v156, v157, v158, s[0:1]
	v_mul_f32_e32 v157, 0x37800000, v156
	v_cndmask_b32_e32 v156, v156, v157, vcc
	v_cmp_class_f32_e32 vcc, v3, v218
	s_nop 1
	v_cndmask_b32_e32 v3, v156, v3, vcc
	v_div_scale_f32 v156, s[0:1], v3, v3, 1.0
	v_rcp_f32_e32 v157, v156
	s_nop 0
	v_fma_f32 v158, -v156, v157, 1.0
	v_fmac_f32_e32 v157, v158, v157
	v_div_scale_f32 v158, vcc, 1.0, v3, 1.0
	v_mul_f32_e32 v159, v158, v157
	v_fma_f32 v189, -v156, v159, v158
	v_fmac_f32_e32 v159, v189, v157
	v_fma_f32 v156, -v156, v159, v158
	v_div_fmas_f32 v156, v156, v157, v159
	v_div_fixup_f32 v3, v156, v3, 1.0
	v_lshl_add_u32 v156, v0, 2, 0
	v_add_u32_e32 v156, 0x22c00, v156
	ds_write_b32 v156, v3

.LBB0_770:
	s_or_b64 exec, exec, s[0:1]
	v_readlane_b32 s0, v255, 39
	v_readlane_b32 s1, v255, 40
	s_nop 1
	v_lshl_add_u64 v[136:137], v[190:191], 2, s[0:1]
	global_load_dwordx4 v[140:143], v[136:137], off offset:16
	global_load_dwordx4 v[144:147], v[136:137], off
	global_load_dwordx4 v[132:135], v[136:137], off offset:528
	s_nop 0
	global_load_dwordx4 v[136:139], v[136:137], off offset:512
	s_waitcnt vmcnt(0)
	s_waitcnt lgkmcnt(0)
	s_mov_b64 s[0:1], exec
	s_branch .LBB0_795

.LBB0_795:
	s_or_b64 exec, exec, s[0:1]
	s_and_saveexec_b64 s[2:3], s[4:5]
	s_cbranch_execz .LBB0_797
	v_lshl_add_u64 v[148:149], v[192:193], 4, s[62:63]
	s_movk_i32 s81, 0x1000
	s_mov_b64 s[10:11], exec
.Lx2_spin:
	global_load_dword v152, v[148:149], off sc1
	global_load_dword v154, v[148:149], off offset:4 sc1
	global_load_dword v153, v[148:149], off offset:8 sc1
	global_load_dword v155, v[148:149], off offset:12 sc1
	s_waitcnt vmcnt(0)
	v_cmp_u_f32_e32 vcc, v152, v154
	v_cmp_u_f32_e64 s[38:39], v153, v155
	s_or_b64 vcc, vcc, s[38:39]
	s_add_i32 s81, s81, -1
	s_cmp_eq_u32 s81, 0
	s_cbranch_scc1 .Lx2_done
	s_and_b64 exec, exec, vcc
	s_cbranch_execz .Lx2_done
	s_sleep 1
	s_branch .Lx2_spin
.Lx2_done:
	s_mov_b64 exec, s[10:11]
	s_mov_b32 s0, 0xf800000
	v_lshl_add_u32 v0, v0, 2, 0
	v_add_u32_e32 v0, 0x22c00, v0
	s_waitcnt lgkmcnt(0)
	v_pk_add_f32 v[148:149], v[152:153], v[154:155]
	s_nop 0
	v_add_f32_e32 v148, v148, v149
	v_fmamk_f32 v148, v148, 0x3a800000, v217
	v_mul_f32_e32 v149, 0x4f800000, v148
	v_cmp_gt_f32_e32 vcc, s0, v148
	s_nop 1
	v_cndmask_b32_e32 v148, v148, v149, vcc
	v_sqrt_f32_e32 v149, v148
	s_nop 0
	v_add_u32_e32 v151, -1, v149
	v_add_u32_e32 v152, 1, v149
	v_fma_f32 v153, -v151, v149, v148
	v_fma_f32 v154, -v152, v149, v148
	v_cmp_ge_f32_e64 s[0:1], 0, v153
	s_nop 1
	v_cndmask_b32_e64 v149, v149, v151, s[0:1]
	v_cmp_lt_f32_e64 s[0:1], 0, v154
	s_nop 1
	v_cndmask_b32_e64 v149, v149, v152, s[0:1]
	v_mul_f32_e32 v151, 0x37800000, v149
	v_cndmask_b32_e32 v149, v149, v151, vcc
	v_cmp_class_f32_e32 vcc, v148, v218
	s_nop 1
	v_cndmask_b32_e32 v148, v149, v148, vcc
	v_div_scale_f32 v149, s[0:1], v148, v148, 1.0
	v_rcp_f32_e32 v151, v149
	v_div_scale_f32 v152, vcc, 1.0, v148, 1.0
	v_fma_f32 v153, -v149, v151, 1.0
	v_fmac_f32_e32 v151, v153, v151
	v_mul_f32_e32 v153, v152, v151
	v_fma_f32 v154, -v149, v153, v152
	v_fmac_f32_e32 v153, v154, v151
	v_fma_f32 v149, -v149, v153, v152
	v_div_fmas_f32 v149, v149, v151, v153
	v_div_fixup_f32 v148, v149, v148, 1.0
	ds_write_b32 v0, v148
